# silu(z) computed once in the in-proj GEMM epilogue (z tiles) instead of per chunk in the GDN scan finalizer
# baseline (speedup 1.0000x reference)
.Lgemm_epi2:
	s_sub_u32 s0, s4, 6
	s_cmp_lt_u32 s0, 2
	s_cbranch_scc0 .Lsilu_skip_p3
	s_lshl_b32 s0, s5, 10
	v_add_u32_e32 v224, s0, v162
	ds_read_b32 v208, v224
	ds_read_b32 v210, v224 offset:64
	ds_read_b32 v212, v224 offset:128
	ds_read_b32 v214, v224 offset:192
	ds_read_b32 v216, v224 offset:512
	ds_read_b32 v218, v224 offset:576
	ds_read_b32 v220, v224 offset:640
	ds_read_b32 v222, v224 offset:704
	s_mov_b32 s0, 0xbfb8aa3b
	s_waitcnt lgkmcnt(0)
	v_mul_f32_e32 v208, s0, v208
	v_mul_f32_e32 v210, s0, v210
	v_mul_f32_e32 v212, s0, v212
	v_mul_f32_e32 v214, s0, v214
	v_mul_f32_e32 v216, s0, v216
	v_mul_f32_e32 v218, s0, v218
	v_mul_f32_e32 v220, s0, v220
	v_mul_f32_e32 v222, s0, v222
	v_pk_mul_f32 v[200:201], v[114:115], v[208:209] op_sel_hi:[1,0]
	v_pk_mul_f32 v[202:203], v[116:117], v[208:209] op_sel_hi:[1,0]
	v_pk_mul_f32 v[204:205], v[118:119], v[208:209] op_sel_hi:[1,0]
	v_pk_mul_f32 v[206:207], v[120:121], v[208:209] op_sel_hi:[1,0]
	v_exp_f32_e32 v200, v200
	v_exp_f32_e32 v201, v201
	v_exp_f32_e32 v202, v202
	v_exp_f32_e32 v203, v203
	v_exp_f32_e32 v204, v204
	v_exp_f32_e32 v205, v205
	v_exp_f32_e32 v206, v206
	v_exp_f32_e32 v207, v207
	v_pk_add_f32 v[200:201], v[200:201], 1.0 op_sel_hi:[1,0]
	v_pk_add_f32 v[202:203], v[202:203], 1.0 op_sel_hi:[1,0]
	v_pk_add_f32 v[204:205], v[204:205], 1.0 op_sel_hi:[1,0]
	v_pk_add_f32 v[206:207], v[206:207], 1.0 op_sel_hi:[1,0]
	v_rcp_f32_e32 v200, v200
	v_rcp_f32_e32 v201, v201
	v_rcp_f32_e32 v202, v202
	v_rcp_f32_e32 v203, v203
	v_rcp_f32_e32 v204, v204
	v_rcp_f32_e32 v205, v205
	v_rcp_f32_e32 v206, v206
	v_rcp_f32_e32 v207, v207
	v_pk_mul_f32 v[114:115], v[114:115], v[200:201]
	v_pk_mul_f32 v[116:117], v[116:117], v[202:203]
	v_pk_mul_f32 v[118:119], v[118:119], v[204:205]
	v_pk_mul_f32 v[120:121], v[120:121], v[206:207]
	v_pk_mul_f32 v[200:201], v[122:123], v[208:209] op_sel_hi:[1,0]
	v_pk_mul_f32 v[202:203], v[124:125], v[208:209] op_sel_hi:[1,0]
	v_pk_mul_f32 v[204:205], v[126:127], v[208:209] op_sel_hi:[1,0]
	v_pk_mul_f32 v[206:207], v[128:129], v[208:209] op_sel_hi:[1,0]
	v_exp_f32_e32 v200, v200
	v_exp_f32_e32 v201, v201
	v_exp_f32_e32 v202, v202
	v_exp_f32_e32 v203, v203
	v_exp_f32_e32 v204, v204
	v_exp_f32_e32 v205, v205
	v_exp_f32_e32 v206, v206
	v_exp_f32_e32 v207, v207
	v_pk_add_f32 v[200:201], v[200:201], 1.0 op_sel_hi:[1,0]
	v_pk_add_f32 v[202:203], v[202:203], 1.0 op_sel_hi:[1,0]
	v_pk_add_f32 v[204:205], v[204:205], 1.0 op_sel_hi:[1,0]
	v_pk_add_f32 v[206:207], v[206:207], 1.0 op_sel_hi:[1,0]
	v_rcp_f32_e32 v200, v200
	v_rcp_f32_e32 v201, v201
	v_rcp_f32_e32 v202, v202
	v_rcp_f32_e32 v203, v203
	v_rcp_f32_e32 v204, v204
	v_rcp_f32_e32 v205, v205
	v_rcp_f32_e32 v206, v206
	v_rcp_f32_e32 v207, v207
	v_pk_mul_f32 v[122:123], v[122:123], v[200:201]
	v_pk_mul_f32 v[124:125], v[124:125], v[202:203]
	v_pk_mul_f32 v[126:127], v[126:127], v[204:205]
	v_pk_mul_f32 v[128:129], v[128:129], v[206:207]
	v_pk_mul_f32 v[200:201], v[98:99], v[210:211] op_sel_hi:[1,0]
	v_pk_mul_f32 v[202:203], v[100:101], v[210:211] op_sel_hi:[1,0]
	v_pk_mul_f32 v[204:205], v[102:103], v[210:211] op_sel_hi:[1,0]
	v_pk_mul_f32 v[206:207], v[104:105], v[210:211] op_sel_hi:[1,0]
	v_exp_f32_e32 v200, v200
	v_exp_f32_e32 v201, v201
	v_exp_f32_e32 v202, v202
	v_exp_f32_e32 v203, v203
	v_exp_f32_e32 v204, v204
	v_exp_f32_e32 v205, v205
	v_exp_f32_e32 v206, v206
	v_exp_f32_e32 v207, v207
	v_pk_add_f32 v[200:201], v[200:201], 1.0 op_sel_hi:[1,0]
	v_pk_add_f32 v[202:203], v[202:203], 1.0 op_sel_hi:[1,0]
	v_pk_add_f32 v[204:205], v[204:205], 1.0 op_sel_hi:[1,0]
	v_pk_add_f32 v[206:207], v[206:207], 1.0 op_sel_hi:[1,0]
	v_rcp_f32_e32 v200, v200
	v_rcp_f32_e32 v201, v201
	v_rcp_f32_e32 v202, v202
	v_rcp_f32_e32 v203, v203
	v_rcp_f32_e32 v204, v204
	v_rcp_f32_e32 v205, v205
	v_rcp_f32_e32 v206, v206
	v_rcp_f32_e32 v207, v207
	v_pk_mul_f32 v[98:99], v[98:99], v[200:201]
	v_pk_mul_f32 v[100:101], v[100:101], v[202:203]
	v_pk_mul_f32 v[102:103], v[102:103], v[204:205]
	v_pk_mul_f32 v[104:105], v[104:105], v[206:207]
	v_pk_mul_f32 v[200:201], v[106:107], v[210:211] op_sel_hi:[1,0]
	v_pk_mul_f32 v[202:203], v[108:109], v[210:211] op_sel_hi:[1,0]
	v_pk_mul_f32 v[204:205], v[110:111], v[210:211] op_sel_hi:[1,0]
	v_pk_mul_f32 v[206:207], v[112:113], v[210:211] op_sel_hi:[1,0]
	v_exp_f32_e32 v200, v200
	v_exp_f32_e32 v201, v201
	v_exp_f32_e32 v202, v202
	v_exp_f32_e32 v203, v203
	v_exp_f32_e32 v204, v204
	v_exp_f32_e32 v205, v205
	v_exp_f32_e32 v206, v206
	v_exp_f32_e32 v207, v207
	v_pk_add_f32 v[200:201], v[200:201], 1.0 op_sel_hi:[1,0]
	v_pk_add_f32 v[202:203], v[202:203], 1.0 op_sel_hi:[1,0]
	v_pk_add_f32 v[204:205], v[204:205], 1.0 op_sel_hi:[1,0]
	v_pk_add_f32 v[206:207], v[206:207], 1.0 op_sel_hi:[1,0]
	v_rcp_f32_e32 v200, v200
	v_rcp_f32_e32 v201, v201
	v_rcp_f32_e32 v202, v202
	v_rcp_f32_e32 v203, v203
	v_rcp_f32_e32 v204, v204
	v_rcp_f32_e32 v205, v205
	v_rcp_f32_e32 v206, v206
	v_rcp_f32_e32 v207, v207
	v_pk_mul_f32 v[106:107], v[106:107], v[200:201]
	v_pk_mul_f32 v[108:109], v[108:109], v[202:203]
	v_pk_mul_f32 v[110:111], v[110:111], v[204:205]
	v_pk_mul_f32 v[112:113], v[112:113], v[206:207]
	v_pk_mul_f32 v[200:201], v[82:83], v[212:213] op_sel_hi:[1,0]
	v_pk_mul_f32 v[202:203], v[84:85], v[212:213] op_sel_hi:[1,0]
	v_pk_mul_f32 v[204:205], v[86:87], v[212:213] op_sel_hi:[1,0]
	v_pk_mul_f32 v[206:207], v[88:89], v[212:213] op_sel_hi:[1,0]
	v_exp_f32_e32 v200, v200
	v_exp_f32_e32 v201, v201
	v_exp_f32_e32 v202, v202
	v_exp_f32_e32 v203, v203
	v_exp_f32_e32 v204, v204
	v_exp_f32_e32 v205, v205
	v_exp_f32_e32 v206, v206
	v_exp_f32_e32 v207, v207
	v_pk_add_f32 v[200:201], v[200:201], 1.0 op_sel_hi:[1,0]
	v_pk_add_f32 v[202:203], v[202:203], 1.0 op_sel_hi:[1,0]
	v_pk_add_f32 v[204:205], v[204:205], 1.0 op_sel_hi:[1,0]
	v_pk_add_f32 v[206:207], v[206:207], 1.0 op_sel_hi:[1,0]
	v_rcp_f32_e32 v200, v200
	v_rcp_f32_e32 v201, v201
	v_rcp_f32_e32 v202, v202
	v_rcp_f32_e32 v203, v203
	v_rcp_f32_e32 v204, v204
	v_rcp_f32_e32 v205, v205
	v_rcp_f32_e32 v206, v206
	v_rcp_f32_e32 v207, v207
	v_pk_mul_f32 v[82:83], v[82:83], v[200:201]
	v_pk_mul_f32 v[84:85], v[84:85], v[202:203]
	v_pk_mul_f32 v[86:87], v[86:87], v[204:205]
	v_pk_mul_f32 v[88:89], v[88:89], v[206:207]
	v_pk_mul_f32 v[200:201], v[90:91], v[212:213] op_sel_hi:[1,0]
	v_pk_mul_f32 v[202:203], v[92:93], v[212:213] op_sel_hi:[1,0]
	v_pk_mul_f32 v[204:205], v[94:95], v[212:213] op_sel_hi:[1,0]
	v_pk_mul_f32 v[206:207], v[96:97], v[212:213] op_sel_hi:[1,0]
	v_exp_f32_e32 v200, v200
	v_exp_f32_e32 v201, v201
	v_exp_f32_e32 v202, v202
	v_exp_f32_e32 v203, v203
	v_exp_f32_e32 v204, v204
	v_exp_f32_e32 v205, v205
	v_exp_f32_e32 v206, v206
	v_exp_f32_e32 v207, v207
	v_pk_add_f32 v[200:201], v[200:201], 1.0 op_sel_hi:[1,0]
	v_pk_add_f32 v[202:203], v[202:203], 1.0 op_sel_hi:[1,0]
	v_pk_add_f32 v[204:205], v[204:205], 1.0 op_sel_hi:[1,0]
	v_pk_add_f32 v[206:207], v[206:207], 1.0 op_sel_hi:[1,0]
	v_rcp_f32_e32 v200, v200
	v_rcp_f32_e32 v201, v201
	v_rcp_f32_e32 v202, v202
	v_rcp_f32_e32 v203, v203
	v_rcp_f32_e32 v204, v204
	v_rcp_f32_e32 v205, v205
	v_rcp_f32_e32 v206, v206
	v_rcp_f32_e32 v207, v207
	v_pk_mul_f32 v[90:91], v[90:91], v[200:201]
	v_pk_mul_f32 v[92:93], v[92:93], v[202:203]
	v_pk_mul_f32 v[94:95], v[94:95], v[204:205]
	v_pk_mul_f32 v[96:97], v[96:97], v[206:207]
	v_pk_mul_f32 v[200:201], v[66:67], v[214:215] op_sel_hi:[1,0]
	v_pk_mul_f32 v[202:203], v[68:69], v[214:215] op_sel_hi:[1,0]
	v_pk_mul_f32 v[204:205], v[70:71], v[214:215] op_sel_hi:[1,0]
	v_pk_mul_f32 v[206:207], v[72:73], v[214:215] op_sel_hi:[1,0]
	v_exp_f32_e32 v200, v200
	v_exp_f32_e32 v201, v201
	v_exp_f32_e32 v202, v202
	v_exp_f32_e32 v203, v203
	v_exp_f32_e32 v204, v204
	v_exp_f32_e32 v205, v205
	v_exp_f32_e32 v206, v206
	v_exp_f32_e32 v207, v207
	v_pk_add_f32 v[200:201], v[200:201], 1.0 op_sel_hi:[1,0]
	v_pk_add_f32 v[202:203], v[202:203], 1.0 op_sel_hi:[1,0]
	v_pk_add_f32 v[204:205], v[204:205], 1.0 op_sel_hi:[1,0]
	v_pk_add_f32 v[206:207], v[206:207], 1.0 op_sel_hi:[1,0]
	v_rcp_f32_e32 v200, v200
	v_rcp_f32_e32 v201, v201
	v_rcp_f32_e32 v202, v202
	v_rcp_f32_e32 v203, v203
	v_rcp_f32_e32 v204, v204
	v_rcp_f32_e32 v205, v205
	v_rcp_f32_e32 v206, v206
	v_rcp_f32_e32 v207, v207
	v_pk_mul_f32 v[66:67], v[66:67], v[200:201]
	v_pk_mul_f32 v[68:69], v[68:69], v[202:203]
	v_pk_mul_f32 v[70:71], v[70:71], v[204:205]
	v_pk_mul_f32 v[72:73], v[72:73], v[206:207]
	v_pk_mul_f32 v[200:201], v[74:75], v[214:215] op_sel_hi:[1,0]
	v_pk_mul_f32 v[202:203], v[76:77], v[214:215] op_sel_hi:[1,0]
	v_pk_mul_f32 v[204:205], v[78:79], v[214:215] op_sel_hi:[1,0]
	v_pk_mul_f32 v[206:207], v[80:81], v[214:215] op_sel_hi:[1,0]
	v_exp_f32_e32 v200, v200
	v_exp_f32_e32 v201, v201
	v_exp_f32_e32 v202, v202
	v_exp_f32_e32 v203, v203
	v_exp_f32_e32 v204, v204
	v_exp_f32_e32 v205, v205
	v_exp_f32_e32 v206, v206
	v_exp_f32_e32 v207, v207
	v_pk_add_f32 v[200:201], v[200:201], 1.0 op_sel_hi:[1,0]
	v_pk_add_f32 v[202:203], v[202:203], 1.0 op_sel_hi:[1,0]
	v_pk_add_f32 v[204:205], v[204:205], 1.0 op_sel_hi:[1,0]
	v_pk_add_f32 v[206:207], v[206:207], 1.0 op_sel_hi:[1,0]
	v_rcp_f32_e32 v200, v200
	v_rcp_f32_e32 v201, v201
	v_rcp_f32_e32 v202, v202
	v_rcp_f32_e32 v203, v203
	v_rcp_f32_e32 v204, v204
	v_rcp_f32_e32 v205, v205
	v_rcp_f32_e32 v206, v206
	v_rcp_f32_e32 v207, v207
	v_pk_mul_f32 v[74:75], v[74:75], v[200:201]
	v_pk_mul_f32 v[76:77], v[76:77], v[202:203]
	v_pk_mul_f32 v[78:79], v[78:79], v[204:205]
	v_pk_mul_f32 v[80:81], v[80:81], v[206:207]
	v_pk_mul_f32 v[200:201], v[50:51], v[216:217] op_sel_hi:[1,0]
	v_pk_mul_f32 v[202:203], v[52:53], v[216:217] op_sel_hi:[1,0]
	v_pk_mul_f32 v[204:205], v[54:55], v[216:217] op_sel_hi:[1,0]
	v_pk_mul_f32 v[206:207], v[56:57], v[216:217] op_sel_hi:[1,0]
	v_exp_f32_e32 v200, v200
	v_exp_f32_e32 v201, v201
	v_exp_f32_e32 v202, v202
	v_exp_f32_e32 v203, v203
	v_exp_f32_e32 v204, v204
	v_exp_f32_e32 v205, v205
	v_exp_f32_e32 v206, v206
	v_exp_f32_e32 v207, v207
	v_pk_add_f32 v[200:201], v[200:201], 1.0 op_sel_hi:[1,0]
	v_pk_add_f32 v[202:203], v[202:203], 1.0 op_sel_hi:[1,0]
	v_pk_add_f32 v[204:205], v[204:205], 1.0 op_sel_hi:[1,0]
	v_pk_add_f32 v[206:207], v[206:207], 1.0 op_sel_hi:[1,0]
	v_rcp_f32_e32 v200, v200
	v_rcp_f32_e32 v201, v201
	v_rcp_f32_e32 v202, v202
	v_rcp_f32_e32 v203, v203
	v_rcp_f32_e32 v204, v204
	v_rcp_f32_e32 v205, v205
	v_rcp_f32_e32 v206, v206
	v_rcp_f32_e32 v207, v207
	v_pk_mul_f32 v[50:51], v[50:51], v[200:201]
	v_pk_mul_f32 v[52:53], v[52:53], v[202:203]
	v_pk_mul_f32 v[54:55], v[54:55], v[204:205]
	v_pk_mul_f32 v[56:57], v[56:57], v[206:207]
	v_pk_mul_f32 v[200:201], v[58:59], v[216:217] op_sel_hi:[1,0]
	v_pk_mul_f32 v[202:203], v[60:61], v[216:217] op_sel_hi:[1,0]
	v_pk_mul_f32 v[204:205], v[62:63], v[216:217] op_sel_hi:[1,0]
	v_pk_mul_f32 v[206:207], v[64:65], v[216:217] op_sel_hi:[1,0]
	v_exp_f32_e32 v200, v200
	v_exp_f32_e32 v201, v201
	v_exp_f32_e32 v202, v202
	v_exp_f32_e32 v203, v203
	v_exp_f32_e32 v204, v204
	v_exp_f32_e32 v205, v205
	v_exp_f32_e32 v206, v206
	v_exp_f32_e32 v207, v207
	v_pk_add_f32 v[200:201], v[200:201], 1.0 op_sel_hi:[1,0]
	v_pk_add_f32 v[202:203], v[202:203], 1.0 op_sel_hi:[1,0]
	v_pk_add_f32 v[204:205], v[204:205], 1.0 op_sel_hi:[1,0]
	v_pk_add_f32 v[206:207], v[206:207], 1.0 op_sel_hi:[1,0]
	v_rcp_f32_e32 v200, v200
	v_rcp_f32_e32 v201, v201
	v_rcp_f32_e32 v202, v202
	v_rcp_f32_e32 v203, v203
	v_rcp_f32_e32 v204, v204
	v_rcp_f32_e32 v205, v205
	v_rcp_f32_e32 v206, v206
	v_rcp_f32_e32 v207, v207
	v_pk_mul_f32 v[58:59], v[58:59], v[200:201]
	v_pk_mul_f32 v[60:61], v[60:61], v[202:203]
	v_pk_mul_f32 v[62:63], v[62:63], v[204:205]
	v_pk_mul_f32 v[64:65], v[64:65], v[206:207]
	v_pk_mul_f32 v[200:201], v[34:35], v[218:219] op_sel_hi:[1,0]
	v_pk_mul_f32 v[202:203], v[36:37], v[218:219] op_sel_hi:[1,0]
	v_pk_mul_f32 v[204:205], v[38:39], v[218:219] op_sel_hi:[1,0]
	v_pk_mul_f32 v[206:207], v[40:41], v[218:219] op_sel_hi:[1,0]
	v_exp_f32_e32 v200, v200
	v_exp_f32_e32 v201, v201
	v_exp_f32_e32 v202, v202
	v_exp_f32_e32 v203, v203
	v_exp_f32_e32 v204, v204
	v_exp_f32_e32 v205, v205
	v_exp_f32_e32 v206, v206
	v_exp_f32_e32 v207, v207
	v_pk_add_f32 v[200:201], v[200:201], 1.0 op_sel_hi:[1,0]
	v_pk_add_f32 v[202:203], v[202:203], 1.0 op_sel_hi:[1,0]
	v_pk_add_f32 v[204:205], v[204:205], 1.0 op_sel_hi:[1,0]
	v_pk_add_f32 v[206:207], v[206:207], 1.0 op_sel_hi:[1,0]
	v_rcp_f32_e32 v200, v200
	v_rcp_f32_e32 v201, v201
	v_rcp_f32_e32 v202, v202
	v_rcp_f32_e32 v203, v203
	v_rcp_f32_e32 v204, v204
	v_rcp_f32_e32 v205, v205
	v_rcp_f32_e32 v206, v206
	v_rcp_f32_e32 v207, v207
	v_pk_mul_f32 v[34:35], v[34:35], v[200:201]
	v_pk_mul_f32 v[36:37], v[36:37], v[202:203]
	v_pk_mul_f32 v[38:39], v[38:39], v[204:205]
	v_pk_mul_f32 v[40:41], v[40:41], v[206:207]
	v_pk_mul_f32 v[200:201], v[42:43], v[218:219] op_sel_hi:[1,0]
	v_pk_mul_f32 v[202:203], v[44:45], v[218:219] op_sel_hi:[1,0]
	v_pk_mul_f32 v[204:205], v[46:47], v[218:219] op_sel_hi:[1,0]
	v_pk_mul_f32 v[206:207], v[48:49], v[218:219] op_sel_hi:[1,0]
	v_exp_f32_e32 v200, v200
	v_exp_f32_e32 v201, v201
	v_exp_f32_e32 v202, v202
	v_exp_f32_e32 v203, v203
	v_exp_f32_e32 v204, v204
	v_exp_f32_e32 v205, v205
	v_exp_f32_e32 v206, v206
	v_exp_f32_e32 v207, v207
	v_pk_add_f32 v[200:201], v[200:201], 1.0 op_sel_hi:[1,0]
	v_pk_add_f32 v[202:203], v[202:203], 1.0 op_sel_hi:[1,0]
	v_pk_add_f32 v[204:205], v[204:205], 1.0 op_sel_hi:[1,0]
	v_pk_add_f32 v[206:207], v[206:207], 1.0 op_sel_hi:[1,0]
	v_rcp_f32_e32 v200, v200
	v_rcp_f32_e32 v201, v201
	v_rcp_f32_e32 v202, v202
	v_rcp_f32_e32 v203, v203
	v_rcp_f32_e32 v204, v204
	v_rcp_f32_e32 v205, v205
	v_rcp_f32_e32 v206, v206
	v_rcp_f32_e32 v207, v207
	v_pk_mul_f32 v[42:43], v[42:43], v[200:201]
	v_pk_mul_f32 v[44:45], v[44:45], v[202:203]
	v_pk_mul_f32 v[46:47], v[46:47], v[204:205]
	v_pk_mul_f32 v[48:49], v[48:49], v[206:207]
	v_pk_mul_f32 v[200:201], v[18:19], v[220:221] op_sel_hi:[1,0]
	v_pk_mul_f32 v[202:203], v[20:21], v[220:221] op_sel_hi:[1,0]
	v_pk_mul_f32 v[204:205], v[22:23], v[220:221] op_sel_hi:[1,0]
	v_pk_mul_f32 v[206:207], v[24:25], v[220:221] op_sel_hi:[1,0]
	v_exp_f32_e32 v200, v200
	v_exp_f32_e32 v201, v201
	v_exp_f32_e32 v202, v202
	v_exp_f32_e32 v203, v203
	v_exp_f32_e32 v204, v204
	v_exp_f32_e32 v205, v205
	v_exp_f32_e32 v206, v206
	v_exp_f32_e32 v207, v207
	v_pk_add_f32 v[200:201], v[200:201], 1.0 op_sel_hi:[1,0]
	v_pk_add_f32 v[202:203], v[202:203], 1.0 op_sel_hi:[1,0]
	v_pk_add_f32 v[204:205], v[204:205], 1.0 op_sel_hi:[1,0]
	v_pk_add_f32 v[206:207], v[206:207], 1.0 op_sel_hi:[1,0]
	v_rcp_f32_e32 v200, v200
	v_rcp_f32_e32 v201, v201
	v_rcp_f32_e32 v202, v202
	v_rcp_f32_e32 v203, v203
	v_rcp_f32_e32 v204, v204
	v_rcp_f32_e32 v205, v205
	v_rcp_f32_e32 v206, v206
	v_rcp_f32_e32 v207, v207
	v_pk_mul_f32 v[18:19], v[18:19], v[200:201]
	v_pk_mul_f32 v[20:21], v[20:21], v[202:203]
	v_pk_mul_f32 v[22:23], v[22:23], v[204:205]
	v_pk_mul_f32 v[24:25], v[24:25], v[206:207]
	v_pk_mul_f32 v[200:201], v[26:27], v[220:221] op_sel_hi:[1,0]
	v_pk_mul_f32 v[202:203], v[28:29], v[220:221] op_sel_hi:[1,0]
	v_pk_mul_f32 v[204:205], v[30:31], v[220:221] op_sel_hi:[1,0]
	v_pk_mul_f32 v[206:207], v[32:33], v[220:221] op_sel_hi:[1,0]
	v_exp_f32_e32 v200, v200
	v_exp_f32_e32 v201, v201
	v_exp_f32_e32 v202, v202
	v_exp_f32_e32 v203, v203
	v_exp_f32_e32 v204, v204
	v_exp_f32_e32 v205, v205
	v_exp_f32_e32 v206, v206
	v_exp_f32_e32 v207, v207
	v_pk_add_f32 v[200:201], v[200:201], 1.0 op_sel_hi:[1,0]
	v_pk_add_f32 v[202:203], v[202:203], 1.0 op_sel_hi:[1,0]
	v_pk_add_f32 v[204:205], v[204:205], 1.0 op_sel_hi:[1,0]
	v_pk_add_f32 v[206:207], v[206:207], 1.0 op_sel_hi:[1,0]
	v_rcp_f32_e32 v200, v200
	v_rcp_f32_e32 v201, v201
	v_rcp_f32_e32 v202, v202
	v_rcp_f32_e32 v203, v203
	v_rcp_f32_e32 v204, v204
	v_rcp_f32_e32 v205, v205
	v_rcp_f32_e32 v206, v206
	v_rcp_f32_e32 v207, v207
	v_pk_mul_f32 v[26:27], v[26:27], v[200:201]
	v_pk_mul_f32 v[28:29], v[28:29], v[202:203]
	v_pk_mul_f32 v[30:31], v[30:31], v[204:205]
	v_pk_mul_f32 v[32:33], v[32:33], v[206:207]
	v_pk_mul_f32 v[200:201], v[2:3], v[222:223] op_sel_hi:[1,0]
	v_pk_mul_f32 v[202:203], v[4:5], v[222:223] op_sel_hi:[1,0]
	v_pk_mul_f32 v[204:205], v[6:7], v[222:223] op_sel_hi:[1,0]
	v_pk_mul_f32 v[206:207], v[8:9], v[222:223] op_sel_hi:[1,0]
	v_exp_f32_e32 v200, v200
	v_exp_f32_e32 v201, v201
	v_exp_f32_e32 v202, v202
	v_exp_f32_e32 v203, v203
	v_exp_f32_e32 v204, v204
	v_exp_f32_e32 v205, v205
	v_exp_f32_e32 v206, v206
	v_exp_f32_e32 v207, v207
	v_pk_add_f32 v[200:201], v[200:201], 1.0 op_sel_hi:[1,0]
	v_pk_add_f32 v[202:203], v[202:203], 1.0 op_sel_hi:[1,0]
	v_pk_add_f32 v[204:205], v[204:205], 1.0 op_sel_hi:[1,0]
	v_pk_add_f32 v[206:207], v[206:207], 1.0 op_sel_hi:[1,0]
	v_rcp_f32_e32 v200, v200
	v_rcp_f32_e32 v201, v201
	v_rcp_f32_e32 v202, v202
	v_rcp_f32_e32 v203, v203
	v_rcp_f32_e32 v204, v204
	v_rcp_f32_e32 v205, v205
	v_rcp_f32_e32 v206, v206
	v_rcp_f32_e32 v207, v207
	v_pk_mul_f32 v[2:3], v[2:3], v[200:201]
	v_pk_mul_f32 v[4:5], v[4:5], v[202:203]
	v_pk_mul_f32 v[6:7], v[6:7], v[204:205]
	v_pk_mul_f32 v[8:9], v[8:9], v[206:207]
	v_pk_mul_f32 v[200:201], v[10:11], v[222:223] op_sel_hi:[1,0]
	v_pk_mul_f32 v[202:203], v[12:13], v[222:223] op_sel_hi:[1,0]
	v_pk_mul_f32 v[204:205], v[14:15], v[222:223] op_sel_hi:[1,0]
	v_pk_mul_f32 v[206:207], v[16:17], v[222:223] op_sel_hi:[1,0]
	v_exp_f32_e32 v200, v200
	v_exp_f32_e32 v201, v201
	v_exp_f32_e32 v202, v202
	v_exp_f32_e32 v203, v203
	v_exp_f32_e32 v204, v204
	v_exp_f32_e32 v205, v205
	v_exp_f32_e32 v206, v206
	v_exp_f32_e32 v207, v207
	v_pk_add_f32 v[200:201], v[200:201], 1.0 op_sel_hi:[1,0]
	v_pk_add_f32 v[202:203], v[202:203], 1.0 op_sel_hi:[1,0]
	v_pk_add_f32 v[204:205], v[204:205], 1.0 op_sel_hi:[1,0]
	v_pk_add_f32 v[206:207], v[206:207], 1.0 op_sel_hi:[1,0]
	v_rcp_f32_e32 v200, v200
	v_rcp_f32_e32 v201, v201
	v_rcp_f32_e32 v202, v202
	v_rcp_f32_e32 v203, v203
	v_rcp_f32_e32 v204, v204
	v_rcp_f32_e32 v205, v205
	v_rcp_f32_e32 v206, v206
	v_rcp_f32_e32 v207, v207
	v_pk_mul_f32 v[10:11], v[10:11], v[200:201]
	v_pk_mul_f32 v[12:13], v[12:13], v[202:203]
	v_pk_mul_f32 v[14:15], v[14:15], v[204:205]
	v_pk_mul_f32 v[16:17], v[16:17], v[206:207]

.Lscan_top_w1:
	s_waitcnt lgkmcnt(0)
	s_barrier
	s_andn2_b64 vcc, exec, s[22:23]
	s_cbranch_vccnz .LBB0_445
	s_min_u32 s0, s29, 1
	s_sub_i32 s1, s29, s0
	s_lshl_b32 s0, s0, 6
	v_subrev_u32_e32 v2, s0, v203
	s_and_b32 s0, s1, 1
	v_lshl_add_u32 v205, s0, 10, v199
	ds_read2_b32 v[4:5], v205 offset1:16
	ds_read2_b32 v[120:121], v205 offset0:128 offset1:144
	ds_read2_b32 v[122:123], v205 offset0:64 offset1:80
	ds_read2_b32 v[134:135], v205 offset0:192 offset1:208
	v_lshl_add_u32 v204, s0, 14, v182
	s_waitcnt lgkmcnt(0)
	v_mov_b32_e32 v102, v4
	v_mov_b32_e32 v103, v120
	v_mov_b32_e32 v104, v122
	v_mov_b32_e32 v105, v134
	v_add_u32_e32 v4, v204, v186
	s_waitcnt vmcnt(4)
	v_lshlrev_b32_e32 v114, 16, v170
	v_pk_add_f32 v[136:137], v[102:103], v[104:105]
	ds_read_b128 v[116:119], v4
	ds_read_b128 v[102:105], v183
	v_and_b32_e32 v115, 0xffff0000, v170
	ds_read_b128 v[106:109], v183 offset:16
	v_add_u32_e32 v4, v204, v188
	ds_read_b128 v[110:113], v4
	s_waitcnt lgkmcnt(3)
	v_lshlrev_b32_e32 v206, 16, v116
	v_lshlrev_b32_e32 v124, 16, v171
	v_and_b32_e32 v125, 0xffff0000, v171
	v_and_b32_e32 v207, 0xffff0000, v116
	v_lshlrev_b32_e32 v128, 16, v168
	v_and_b32_e32 v129, 0xffff0000, v168
	v_lshlrev_b32_e32 v168, 16, v169
	v_lshlrev_b32_e32 v126, 16, v118
	v_and_b32_e32 v127, 0xffff0000, v118
	v_and_b32_e32 v169, 0xffff0000, v169
	v_mov_b32_e32 v120, v5
	v_mov_b32_e32 v134, v123
	v_mov_b64_e32 v[132:133], v[128:129]
	v_lshlrev_b32_e32 v130, 16, v119
	v_and_b32_e32 v131, 0xffff0000, v119
	v_pk_add_f32 v[118:119], v[120:121], v[134:135]
	v_mov_b32_e32 v121, v136
	v_mov_b32_e32 v120, v118
	v_mov_b32_e32 v136, v119
	v_pk_add_f32 v[118:119], v[120:121], v[136:137]
	v_mov_b64_e32 v[122:123], s[18:19]
	v_pk_fma_f32 v[134:135], v[118:119], s[14:15], v[122:123] op_sel_hi:[1,0,0]
	v_add_u32_e32 v4, s56, v2
	v_mul_f32_e32 v2, 0x4b800000, v135
	v_cmp_gt_f32_e32 vcc, s51, v135
	v_ashrrev_i32_e32 v5, 31, v4
	v_lshlrev_b64 v[118:119], 11, v[4:5]
	v_cndmask_b32_e32 v2, v135, v2, vcc
	v_rsq_f32_e32 v2, v2
	v_mov_b64_e32 v[128:129], v[168:169]
	v_lshlrev_b32_e32 v116, 16, v117
	v_and_b32_e32 v117, 0xffff0000, v117
	v_mul_f32_e32 v5, 0x45800000, v2
	v_cndmask_b32_e32 v2, v2, v5, vcc
	v_pk_mul_f32 v[168:169], v[2:3], v[206:207] op_sel_hi:[0,1]
	s_waitcnt lgkmcnt(2)
	v_pk_mul_f32 v[168:169], v[102:103], v[168:169]
	v_cmp_gt_f32_e32 vcc, s51, v134
	v_pk_mul_f32 v[114:115], v[114:115], v[168:169]
	v_lshl_add_u64 v[136:137], v[150:151], 0, v[118:119]
	v_cvt_pk_bf16_f32 v168, v114, v115
	v_pk_mul_f32 v[114:115], v[2:3], v[116:117] op_sel_hi:[0,1]
	v_pk_mul_f32 v[114:115], v[104:105], v[114:115]
	ds_read_b128 v[118:121], v183
	v_pk_mul_f32 v[114:115], v[124:125], v[114:115]
	v_pk_mul_f32 v[124:125], v[2:3], v[126:127] op_sel_hi:[0,1]
	s_waitcnt lgkmcnt(2)
	v_pk_mul_f32 v[124:125], v[106:107], v[124:125]
	v_cvt_pk_bf16_f32 v169, v114, v115
	v_pk_mul_f32 v[124:125], v[132:133], v[124:125]
	ds_read_b128 v[114:117], v183 offset:16
	v_cvt_pk_bf16_f32 v170, v124, v125
	v_pk_mul_f32 v[124:125], v[2:3], v[130:131] op_sel_hi:[0,1]
	v_mul_f32_e32 v2, 0x4b800000, v134
	v_cndmask_b32_e32 v2, v134, v2, vcc
	v_rsq_f32_e32 v2, v2
	v_pk_mul_f32 v[124:125], v[108:109], v[124:125]
	v_mul_f32_e32 v5, 0x45800000, v2
	v_pk_mul_f32 v[124:125], v[128:129], v[124:125]
	v_cndmask_b32_e32 v2, v2, v5, vcc
	v_cvt_pk_bf16_f32 v171, v124, v125
	v_lshlrev_b32_e32 v124, 16, v164
	v_and_b32_e32 v125, 0xffff0000, v164
	s_waitcnt lgkmcnt(2)
	v_lshlrev_b32_e32 v128, 16, v110
	v_and_b32_e32 v129, 0xffff0000, v110
	v_pk_mul_f32 v[128:129], v[2:3], v[128:129] op_sel_hi:[0,1]
	v_pk_mul_f32 v[128:129], v[102:103], v[128:129]
	v_mov_b64_e32 v[52:53], v[168:169]
	v_mov_b64_e32 v[54:55], v[170:171]
	v_mov_b64_e32 v[56:57], v[136:137]
	v_pk_mul_f32 v[124:125], v[124:125], v[128:129]
	v_lshlrev_b32_e32 v128, 16, v111
	v_cvt_pk_bf16_f32 v110, v124, v125
	v_lshlrev_b32_e32 v124, 16, v165
	v_and_b32_e32 v125, 0xffff0000, v165
	v_and_b32_e32 v129, 0xffff0000, v111
	v_pk_mul_f32 v[128:129], v[2:3], v[128:129] op_sel_hi:[0,1]
	v_pk_mul_f32 v[128:129], v[104:105], v[128:129]
	v_lshlrev_b32_e32 v170, 16, v156
	v_and_b32_e32 v171, 0xffff0000, v156
	v_pk_mul_f32 v[124:125], v[124:125], v[128:129]
	v_lshlrev_b32_e32 v128, 16, v112
	v_cvt_pk_bf16_f32 v111, v124, v125
	v_lshlrev_b32_e32 v124, 16, v160
	v_and_b32_e32 v125, 0xffff0000, v160
	v_and_b32_e32 v129, 0xffff0000, v112
	v_pk_mul_f32 v[128:129], v[2:3], v[128:129] op_sel_hi:[0,1]
	v_pk_mul_f32 v[128:129], v[106:107], v[128:129]
	v_lshlrev_b32_e32 v160, 16, v158
	s_nop 0
	v_pk_mul_f32 v[124:125], v[124:125], v[128:129]
	v_lshlrev_b32_e32 v128, 16, v113
	v_cvt_pk_bf16_f32 v112, v124, v125
	v_lshlrev_b32_e32 v124, 16, v161
	v_and_b32_e32 v125, 0xffff0000, v161
	v_and_b32_e32 v129, 0xffff0000, v113
	v_pk_mul_f32 v[128:129], v[2:3], v[128:129] op_sel_hi:[0,1]
	v_pk_mul_f32 v[128:129], v[108:109], v[128:129]
	v_and_b32_e32 v161, 0xffff0000, v158
	v_pk_mul_f32 v[124:125], v[124:125], v[128:129]
	ds_read2_b32 v[128:129], v205 offset0:32 offset1:48
	ds_read2_b32 v[130:131], v205 offset0:160 offset1:176
	ds_read2_b32 v[132:133], v205 offset0:96 offset1:112
	ds_read2_b32 v[134:135], v205 offset0:224 offset1:240
	v_cvt_pk_bf16_f32 v113, v124, v125
	v_add_u32_e32 v124, 16, v4
	v_ashrrev_i32_e32 v125, 31, v124
	v_lshlrev_b64 v[124:125], 11, v[124:125]
	v_lshl_add_u64 v[124:125], v[150:151], 0, v[124:125]
	v_mov_b64_e32 v[58:59], v[110:111]
	v_mov_b64_e32 v[60:61], v[112:113]
	v_mov_b64_e32 v[62:63], v[124:125]
	v_add_u32_e32 v2, v204, v190
	s_waitcnt lgkmcnt(3)
	v_mov_b32_e32 v110, v128
	s_waitcnt lgkmcnt(2)
	v_mov_b32_e32 v111, v130
	s_waitcnt lgkmcnt(1)
	v_mov_b32_e32 v112, v132
	s_waitcnt lgkmcnt(0)
	v_mov_b32_e32 v113, v134
	v_pk_add_f32 v[136:137], v[110:111], v[112:113]
	ds_read_b128 v[110:113], v2
	v_add_u32_e32 v2, v204, v192
	v_lshlrev_b32_e32 v158, 16, v159
	ds_read_b128 v[124:127], v2
	v_and_b32_e32 v159, 0xffff0000, v159
	v_lshlrev_b32_e32 v204, 16, v157
	v_and_b32_e32 v205, 0xffff0000, v157
	s_waitcnt lgkmcnt(1)
	v_lshlrev_b32_e32 v164, 16, v112
	v_and_b32_e32 v165, 0xffff0000, v112
	v_mov_b32_e32 v130, v129
	v_mov_b32_e32 v134, v133
	v_pk_add_f32 v[130:131], v[130:131], v[134:135]
	v_mov_b32_e32 v133, v136
	v_mov_b32_e32 v132, v130
	v_mov_b32_e32 v136, v131
	v_pk_add_f32 v[130:131], v[132:133], v[136:137]
	v_pk_fma_f32 v[122:123], v[130:131], s[14:15], v[122:123] op_sel_hi:[1,0,0]
	v_mul_f32_e32 v2, 0x4b800000, v123
	v_cmp_gt_f32_e32 vcc, s51, v123
	v_lshlrev_b32_e32 v168, 16, v110
	v_and_b32_e32 v169, 0xffff0000, v110
	v_cndmask_b32_e32 v2, v123, v2, vcc
	v_rsq_f32_e32 v2, v2
	v_lshlrev_b32_e32 v110, 16, v111
	v_and_b32_e32 v111, 0xffff0000, v111
	v_lshlrev_b32_e32 v112, 16, v113
	v_mul_f32_e32 v5, 0x45800000, v2
	v_cndmask_b32_e32 v2, v2, v5, vcc
	v_pk_mul_f32 v[130:131], v[2:3], v[168:169] op_sel_hi:[0,1]
	v_pk_mul_f32 v[110:111], v[2:3], v[110:111] op_sel_hi:[0,1]
	v_pk_mul_f32 v[102:103], v[102:103], v[130:131]
	v_pk_mul_f32 v[104:105], v[104:105], v[110:111]
	v_pk_mul_f32 v[102:103], v[160:161], v[102:103]
	v_pk_mul_f32 v[104:105], v[158:159], v[104:105]
	v_and_b32_e32 v113, 0xffff0000, v113
	v_cvt_pk_bf16_f32 v102, v102, v103
	v_cvt_pk_bf16_f32 v103, v104, v105
	v_pk_mul_f32 v[104:105], v[2:3], v[164:165] op_sel_hi:[0,1]
	v_pk_mul_f32 v[104:105], v[106:107], v[104:105]
	v_pk_mul_f32 v[106:107], v[2:3], v[112:113] op_sel_hi:[0,1]
	v_mul_f32_e32 v2, 0x4b800000, v122
	v_cmp_gt_f32_e32 vcc, s51, v122
	v_add_u32_e32 v128, 32, v4
	v_mov_b64_e32 v[156:157], v[170:171]
	v_cndmask_b32_e32 v2, v122, v2, vcc
	v_rsq_f32_e32 v2, v2
	v_mov_b64_e32 v[170:171], v[204:205]
	v_ashrrev_i32_e32 v129, 31, v128
	v_pk_mul_f32 v[106:107], v[108:109], v[106:107]
	v_lshlrev_b64 v[128:129], 11, v[128:129]
	v_pk_mul_f32 v[104:105], v[156:157], v[104:105]
	v_pk_mul_f32 v[106:107], v[170:171], v[106:107]
	v_lshl_add_u64 v[128:129], v[150:151], 0, v[128:129]
	v_cvt_pk_bf16_f32 v104, v104, v105
	v_cvt_pk_bf16_f32 v105, v106, v107
	v_mov_b64_e32 v[64:65], v[102:103]
	v_mov_b64_e32 v[66:67], v[104:105]
	v_mov_b64_e32 v[68:69], v[128:129]
	v_mul_f32_e32 v5, 0x45800000, v2
	v_cndmask_b32_e32 v2, v2, v5, vcc
	v_lshlrev_b32_e32 v102, 16, v154
	v_and_b32_e32 v103, 0xffff0000, v154
	s_waitcnt lgkmcnt(0)
	v_lshlrev_b32_e32 v106, 16, v124
	v_and_b32_e32 v107, 0xffff0000, v124
	v_pk_mul_f32 v[106:107], v[2:3], v[106:107] op_sel_hi:[0,1]
	v_pk_mul_f32 v[106:107], v[118:119], v[106:107]
	v_lshlrev_b32_e32 v104, 16, v155
	v_pk_mul_f32 v[102:103], v[102:103], v[106:107]
	v_and_b32_e32 v105, 0xffff0000, v155
	v_cvt_pk_bf16_f32 v102, v102, v103
	v_lshlrev_b32_e32 v108, 16, v125
	v_and_b32_e32 v109, 0xffff0000, v125
	v_pk_mul_f32 v[108:109], v[2:3], v[108:109] op_sel_hi:[0,1]
	v_pk_mul_f32 v[108:109], v[120:121], v[108:109]
	v_lshlrev_b32_e32 v110, 16, v127
	v_pk_mul_f32 v[104:105], v[104:105], v[108:109]
	v_lshlrev_b32_e32 v108, 16, v126
	v_cvt_pk_bf16_f32 v103, v104, v105
	v_lshlrev_b32_e32 v104, 16, v152
	v_and_b32_e32 v105, 0xffff0000, v152
	v_and_b32_e32 v109, 0xffff0000, v126
	v_pk_mul_f32 v[108:109], v[2:3], v[108:109] op_sel_hi:[0,1]
	v_pk_mul_f32 v[108:109], v[114:115], v[108:109]
	v_and_b32_e32 v111, 0xffff0000, v127
	v_lshlrev_b32_e32 v106, 16, v153
	v_pk_mul_f32 v[104:105], v[104:105], v[108:109]
	v_and_b32_e32 v107, 0xffff0000, v153
	v_cvt_pk_bf16_f32 v104, v104, v105
	v_pk_mul_f32 v[110:111], v[2:3], v[110:111] op_sel_hi:[0,1]
	v_add_u32_e32 v4, 48, v4
	v_pk_mul_f32 v[110:111], v[116:117], v[110:111]
	v_ashrrev_i32_e32 v5, 31, v4
	v_lshlrev_b64 v[4:5], 11, v[4:5]
	v_pk_mul_f32 v[106:107], v[106:107], v[110:111]
	v_lshl_add_u64 v[4:5], v[150:151], 0, v[4:5]
	v_cvt_pk_bf16_f32 v105, v106, v107
	v_mov_b64_e32 v[70:71], v[102:103]
	v_mov_b64_e32 v[72:73], v[104:105]
	v_mov_b64_e32 v[74:75], v[4:5]

.LBB0_459:
	s_waitcnt vmcnt(0)
	s_setprio 0
	s_and_b64 vcc, exec, s[22:23]
	s_waitcnt vmcnt(0) lgkmcnt(0)
	s_barrier
	s_cbranch_vccz .LBB0_428
	v_add_u32_e32 v2, v194, v186
	v_lshlrev_b32_e32 v16, 16, v170
	ds_read2st64_b32 v[4:5], v195 offset1:1
	ds_read2st64_b32 v[6:7], v195 offset0:2 offset1:3
	ds_read_b128 v[18:21], v2
	v_and_b32_e32 v17, 0xffff0000, v170
	v_lshlrev_b32_e32 v26, 16, v171
	v_and_b32_e32 v27, 0xffff0000, v171
	s_waitcnt lgkmcnt(0)
	v_lshlrev_b32_e32 v40, 16, v18
	v_and_b32_e32 v41, 0xffff0000, v18
	v_lshlrev_b32_e32 v32, 16, v168
	v_and_b32_e32 v33, 0xffff0000, v168
	v_mov_b64_e32 v[30:31], v[26:27]
	v_lshlrev_b32_e32 v24, 16, v169
	v_and_b32_e32 v25, 0xffff0000, v169
	v_lshlrev_b32_e32 v28, 16, v20
	v_and_b32_e32 v29, 0xffff0000, v20
	v_mov_b32_e32 v8, v4
	v_mov_b32_e32 v9, v6
	v_mov_b32_e32 v6, v5
	v_add_u32_e32 v12, v194, v188
	v_pk_add_f32 v[22:23], v[8:9], v[6:7]
	ds_read_b128 v[8:11], v183
	ds_read_b128 v[4:7], v183 offset:16
	ds_read_b128 v[12:15], v12
	v_mov_b64_e32 v[26:27], v[32:33]
	ds_read2st64_b32 v[36:37], v196 offset1:1
	ds_read2st64_b32 v[38:39], v196 offset0:2 offset1:3
	s_or_b32 s0, s21, 0xfc0
	v_or_b32_e32 v20, s0, v140
	v_lshlrev_b32_e32 v34, 16, v21
	v_mov_b64_e32 v[32:33], v[24:25]
	s_waitcnt lgkmcnt(1)
	v_mov_b32_e32 v24, v36
	s_waitcnt lgkmcnt(0)
	v_mov_b32_e32 v25, v38
	v_mov_b32_e32 v38, v37
	v_pk_add_f32 v[24:25], v[24:25], v[38:39]
	v_mov_b32_e32 v37, v22
	v_mov_b32_e32 v36, v24
	v_mov_b32_e32 v22, v25
	v_pk_add_f32 v[22:23], v[36:37], v[22:23]
	v_mov_b64_e32 v[24:25], s[18:19]
	v_pk_fma_f32 v[36:37], v[22:23], s[14:15], v[24:25] op_sel_hi:[1,0,0]
	v_and_b32_e32 v35, 0xffff0000, v21
	v_mul_f32_e32 v2, 0x4b800000, v37
	v_cmp_gt_f32_e32 vcc, s51, v37
	v_ashrrev_i32_e32 v21, 31, v20
	v_lshlrev_b64 v[20:21], 11, v[20:21]
	v_cndmask_b32_e32 v2, v37, v2, vcc
	v_rsq_f32_e32 v2, v2
	v_lshl_add_u64 v[38:39], v[150:151], 0, v[20:21]
	v_lshlrev_b32_e32 v18, 16, v19
	v_and_b32_e32 v19, 0xffff0000, v19
	v_mul_f32_e32 v20, 0x45800000, v2
	v_cndmask_b32_e32 v2, v2, v20, vcc
	v_pk_mul_f32 v[40:41], v[2:3], v[40:41] op_sel_hi:[0,1]
	v_pk_mul_f32 v[28:29], v[2:3], v[28:29] op_sel_hi:[0,1]
	v_pk_mul_f32 v[40:41], v[8:9], v[40:41]
	v_pk_mul_f32 v[28:29], v[4:5], v[28:29]
	v_pk_mul_f32 v[16:17], v[16:17], v[40:41]
	v_pk_mul_f32 v[26:27], v[26:27], v[28:29]
	v_cvt_pk_bf16_f32 v40, v16, v17
	v_pk_mul_f32 v[16:17], v[2:3], v[18:19] op_sel_hi:[0,1]
	v_cvt_pk_bf16_f32 v42, v26, v27
	v_pk_mul_f32 v[26:27], v[2:3], v[34:35] op_sel_hi:[0,1]
	v_mul_f32_e32 v2, 0x4b800000, v36
	v_cmp_gt_f32_e32 vcc, s51, v36
	v_pk_mul_f32 v[26:27], v[6:7], v[26:27]
	v_pk_mul_f32 v[16:17], v[10:11], v[16:17]
	v_cndmask_b32_e32 v2, v36, v2, vcc
	v_rsq_f32_e32 v2, v2
	v_pk_mul_f32 v[26:27], v[32:33], v[26:27]
	v_pk_mul_f32 v[16:17], v[30:31], v[16:17]
	v_cvt_pk_bf16_f32 v43, v26, v27
	v_mul_f32_e32 v26, 0x45800000, v2
	v_cndmask_b32_e32 v2, v2, v26, vcc
	v_lshlrev_b32_e32 v26, 16, v164
	v_and_b32_e32 v27, 0xffff0000, v164
	v_lshlrev_b32_e32 v30, 16, v12
	v_and_b32_e32 v31, 0xffff0000, v12
	v_pk_mul_f32 v[30:31], v[2:3], v[30:31] op_sel_hi:[0,1]
	v_pk_mul_f32 v[30:31], v[8:9], v[30:31]
	v_cvt_pk_bf16_f32 v41, v16, v17
	v_pk_mul_f32 v[26:27], v[26:27], v[30:31]
	v_lshlrev_b32_e32 v30, 16, v13
	v_cvt_pk_bf16_f32 v12, v26, v27
	v_lshlrev_b32_e32 v26, 16, v165
	v_and_b32_e32 v27, 0xffff0000, v165
	v_and_b32_e32 v31, 0xffff0000, v13
	v_pk_mul_f32 v[30:31], v[2:3], v[30:31] op_sel_hi:[0,1]
	v_pk_mul_f32 v[30:31], v[10:11], v[30:31]
	v_lshlrev_b32_e32 v32, 16, v158
	global_store_dwordx4 v[38:39], v[40:43], off
	v_pk_mul_f32 v[26:27], v[26:27], v[30:31]
	v_lshlrev_b32_e32 v30, 16, v14
	v_cvt_pk_bf16_f32 v13, v26, v27
	v_lshlrev_b32_e32 v26, 16, v160
	v_and_b32_e32 v27, 0xffff0000, v160
	v_and_b32_e32 v31, 0xffff0000, v14
	v_pk_mul_f32 v[30:31], v[2:3], v[30:31] op_sel_hi:[0,1]
	v_pk_mul_f32 v[30:31], v[4:5], v[30:31]
	ds_read_b128 v[20:23], v183
	ds_read_b128 v[16:19], v183 offset:16
	v_and_b32_e32 v33, 0xffff0000, v158
	v_pk_mul_f32 v[26:27], v[26:27], v[30:31]
	v_lshlrev_b32_e32 v30, 16, v15
	v_cvt_pk_bf16_f32 v14, v26, v27
	v_lshlrev_b32_e32 v26, 16, v161
	v_and_b32_e32 v27, 0xffff0000, v161
	v_and_b32_e32 v31, 0xffff0000, v15
	v_pk_mul_f32 v[30:31], v[2:3], v[30:31] op_sel_hi:[0,1]
	v_pk_mul_f32 v[30:31], v[6:7], v[30:31]
	v_pk_mul_f32 v[26:27], v[26:27], v[30:31]
	ds_read2st64_b32 v[28:29], v197 offset1:1
	ds_read2st64_b32 v[30:31], v197 offset0:2 offset1:3
	v_cvt_pk_bf16_f32 v15, v26, v27
	v_or_b32_e32 v26, s0, v187
	v_ashrrev_i32_e32 v27, 31, v26
	v_lshlrev_b64 v[26:27], 11, v[26:27]
	v_lshl_add_u64 v[26:27], v[150:151], 0, v[26:27]
	global_store_dwordx4 v[26:27], v[12:15], off
	s_nop 1
	s_waitcnt lgkmcnt(1)
	v_mov_b32_e32 v12, v28
	s_waitcnt lgkmcnt(0)
	v_mov_b32_e32 v13, v30
	v_mov_b32_e32 v30, v29
	v_pk_add_f32 v[30:31], v[12:13], v[30:31]
	v_add_u32_e32 v12, v194, v190
	ds_read_b128 v[12:15], v12
	v_lshlrev_b32_e32 v38, 16, v159
	v_add_u32_e32 v26, v194, v192
	v_and_b32_e32 v39, 0xffff0000, v159
	ds_read_b128 v[26:29], v26
	s_waitcnt lgkmcnt(1)
	v_lshlrev_b32_e32 v36, 16, v12
	v_and_b32_e32 v37, 0xffff0000, v12
	v_lshlrev_b32_e32 v40, 16, v156
	v_lshlrev_b32_e32 v34, 16, v13
	v_and_b32_e32 v35, 0xffff0000, v13
	v_and_b32_e32 v41, 0xffff0000, v156
	ds_read2st64_b32 v[46:47], v198 offset1:1
	ds_read2st64_b32 v[48:49], v198 offset0:2 offset1:3
	v_mov_b64_e32 v[12:13], v[38:39]
	v_lshlrev_b32_e32 v38, 16, v14
	v_lshlrev_b32_e32 v42, 16, v157
	v_and_b32_e32 v43, 0xffff0000, v157
	v_and_b32_e32 v39, 0xffff0000, v14
	s_waitcnt lgkmcnt(1)
	v_mov_b32_e32 v50, v46
	s_waitcnt lgkmcnt(0)
	v_mov_b32_e32 v51, v48
	v_mov_b32_e32 v48, v47
	v_pk_add_f32 v[46:47], v[50:51], v[48:49]
	v_mov_b32_e32 v49, v30
	v_mov_b32_e32 v48, v46
	v_mov_b32_e32 v30, v47
	v_pk_add_f32 v[30:31], v[48:49], v[30:31]
	v_pk_fma_f32 v[24:25], v[30:31], s[14:15], v[24:25] op_sel_hi:[1,0,0]
	v_mul_f32_e32 v2, 0x4b800000, v25
	v_cmp_gt_f32_e32 vcc, s51, v25
	v_lshlrev_b32_e32 v14, 16, v15
	v_and_b32_e32 v15, 0xffff0000, v15
	v_cndmask_b32_e32 v2, v25, v2, vcc
	v_rsq_f32_e32 v2, v2
	v_or_b32_e32 v44, s0, v189
	v_ashrrev_i32_e32 v45, 31, v44
	v_mul_f32_e32 v25, 0x45800000, v2
	v_cndmask_b32_e32 v2, v2, v25, vcc
	v_pk_mul_f32 v[36:37], v[2:3], v[36:37] op_sel_hi:[0,1]
	v_pk_mul_f32 v[8:9], v[8:9], v[36:37]
	v_cmp_gt_f32_e32 vcc, s51, v24
	v_pk_mul_f32 v[8:9], v[32:33], v[8:9]
	v_pk_mul_f32 v[32:33], v[2:3], v[34:35] op_sel_hi:[0,1]
	v_pk_mul_f32 v[10:11], v[10:11], v[32:33]
	v_cvt_pk_bf16_f32 v8, v8, v9
	v_pk_mul_f32 v[10:11], v[12:13], v[10:11]
	v_lshlrev_b64 v[30:31], 11, v[44:45]
	v_cvt_pk_bf16_f32 v9, v10, v11
	v_pk_mul_f32 v[10:11], v[2:3], v[38:39] op_sel_hi:[0,1]
	v_pk_mul_f32 v[4:5], v[4:5], v[10:11]
	v_lshl_add_u64 v[30:31], v[150:151], 0, v[30:31]
	v_pk_mul_f32 v[4:5], v[40:41], v[4:5]
	v_lshlrev_b32_e32 v12, 16, v29
	v_cvt_pk_bf16_f32 v10, v4, v5
	v_pk_mul_f32 v[4:5], v[2:3], v[14:15] op_sel_hi:[0,1]
	v_mul_f32_e32 v2, 0x4b800000, v24
	v_cndmask_b32_e32 v2, v24, v2, vcc
	v_rsq_f32_e32 v2, v2
	v_pk_mul_f32 v[4:5], v[6:7], v[4:5]
	v_and_b32_e32 v13, 0xffff0000, v29
	v_pk_mul_f32 v[4:5], v[42:43], v[4:5]
	s_nop 0
	v_cvt_pk_bf16_f32 v11, v4, v5
	v_mul_f32_e32 v4, 0x45800000, v2
	v_cndmask_b32_e32 v2, v2, v4, vcc
	v_lshlrev_b32_e32 v4, 16, v154
	v_and_b32_e32 v5, 0xffff0000, v154
	global_store_dwordx4 v[30:31], v[8:11], off
	s_nop 1
	v_lshlrev_b32_e32 v8, 16, v26
	v_and_b32_e32 v9, 0xffff0000, v26
	v_pk_mul_f32 v[8:9], v[2:3], v[8:9] op_sel_hi:[0,1]
	v_pk_mul_f32 v[8:9], v[20:21], v[8:9]
	v_lshlrev_b32_e32 v6, 16, v155
	v_pk_mul_f32 v[4:5], v[4:5], v[8:9]
	v_and_b32_e32 v7, 0xffff0000, v155
	v_cvt_pk_bf16_f32 v4, v4, v5
	v_lshlrev_b32_e32 v10, 16, v27
	v_and_b32_e32 v11, 0xffff0000, v27
	v_pk_mul_f32 v[10:11], v[2:3], v[10:11] op_sel_hi:[0,1]
	v_pk_mul_f32 v[10:11], v[22:23], v[10:11]
	v_pk_mul_f32 v[12:13], v[2:3], v[12:13] op_sel_hi:[0,1]
	v_pk_mul_f32 v[6:7], v[6:7], v[10:11]
	v_lshlrev_b32_e32 v10, 16, v28
	v_cvt_pk_bf16_f32 v5, v6, v7
	v_lshlrev_b32_e32 v6, 16, v152
	v_and_b32_e32 v7, 0xffff0000, v152
	v_and_b32_e32 v11, 0xffff0000, v28
	v_pk_mul_f32 v[10:11], v[2:3], v[10:11] op_sel_hi:[0,1]
	v_pk_mul_f32 v[10:11], v[16:17], v[10:11]
	v_pk_mul_f32 v[12:13], v[18:19], v[12:13]
	v_lshlrev_b32_e32 v8, 16, v153
	v_pk_mul_f32 v[6:7], v[6:7], v[10:11]
	v_and_b32_e32 v9, 0xffff0000, v153
	v_cvt_pk_bf16_f32 v6, v6, v7
	s_nop 0
	s_nop 0
	v_pk_mul_f32 v[8:9], v[8:9], v[12:13]
	s_nop 0
	v_cvt_pk_bf16_f32 v7, v8, v9
	v_or_b32_e32 v8, s0, v191
	v_ashrrev_i32_e32 v9, 31, v8
	v_lshlrev_b64 v[8:9], 11, v[8:9]
	v_lshl_add_u64 v[8:9], v[150:151], 0, v[8:9]
	global_store_dwordx4 v[8:9], v[4:7], off
	s_branch .LBB0_428
